# ph_win last half-round moved behind the grid sync with ret_kv items rebalanced; dil_attn and ph_down traverse in reverse order
# speedup vs baseline: 1.0075x; 1.0019x over previous
; DI int opaque_bid() { int t = blockIdx.x; asm volatile("" : "+s"(t)); return t; }
;     DI bool next(int i, Unit& u) const {
;         const long L = (long)i * G + c; if (L >= nwg) return false;
; DI void ph_win(LAS unsigned char* lds, int l, int g) {
;     ...
;     pg8::Gemm gm{(const bf16_t*)(ws + WS_XB) + rb * D, (const bf16_t*)(ws + WS_W + (size_t)l * LW + OW_IN), GT, INW, D}; pg8::StaticOrder S; S.init(GT, INW, gridDim.x, opaque_bid());
;     pg8::EpiZ E{(bf16_t*)(ws + WS_Z), (const float*)(ws + WS_SLOT) + rb * 16, (const float*)(ws + WS_ROPE), (const float*)(ws + WS_ROPE) + SEQ * 64}; pg8::gemm_phase(lds, gm, S, E);
.LBB0_81:
	s_mov_b32 s98, 0
	s_movk_i32 s99, 0x900
	s_mov_b32 s100, 0
.Lwin_again:
	s_waitcnt lgkmcnt(0)
	s_mov_b64 s[4:5], s[0:1]
	s_add_i32 s12, s2, s100
	v_mov_b32_e32 v10, v242
	s_cmpk_lt_i32 s12, 0x980
	s_cselect_b64 s[8:9], -1, 0
	s_cmpk_gt_i32 s12, 0x97f
	v_readfirstlane_b32 s17, v10
	s_cbranch_scc1 .LBB0_83
	s_ashr_i32 s6, s12, 31
	s_lshr_b32 s6, s6, 29
	s_add_i32 s6, s12, s6
	s_ashr_i32 s7, s6, 3
	s_and_b32 s6, s6, -8
	s_sub_i32 s6, s12, s6
	s_cmp_lt_i32 s6, 0
	s_cselect_b32 s18, s74, 0x130
	s_mul_i32 s6, s18, s6
	s_add_i32 s6, s6, s7
	s_mul_hi_i32 s7, s6, 0x6bca1af3
	s_lshr_b32 s18, s7, 31
	s_ashr_i32 s7, s7, 6
	s_add_i32 s7, s7, s18
	s_lshl_b32 s18, s7, 2
	s_mulk_i32 s7, 0x98
	s_sub_i32 s6, s6, s7
	s_bfe_u32 s7, s6, 0x2001d
	s_add_i32 s7, s6, s7
	s_sext_i32_i16 s19, s7
	s_and_b32 s7, s7, 0xfffc
	s_sub_i32 s6, s6, s7
	s_sext_i32_i16 s6, s6
	s_add_i32 s6, s18, s6
	s_ashr_i32 s60, s19, 2

;     DI bool next(int i, Unit& u) const {
;         const long L = (long)i * G + c; if (L >= nwg) return false;
;         int wgid = (int)L; { const int q = nwg / NXCD, r = nwg % NXCD, xcd = wgid % NXCD, off = wgid / NXCD; wgid = (xcd < r ? xcd * (q + 1) : r * (q + 1) + (xcd - r) * q) + off; }
;         const int nig = WGM * nN, gid = wgid / nig, fm = gid * WGM, gsz = (nM - fm) < WGM ? (nM - fm) : WGM;
;         u.pm = fm + ((wgid % nig) % gsz); u.pn = (wgid % nig) / gsz; return true;
;     }
; template <class Epi>
; DI void gemm_phase(LAS unsigned char* lds, const Gemm g, const StaticOrder& S, const Epi& E) {
;     ...
;         const bool has_next = S.next(ui + 1, nxt);
.LBB0_89:
	s_add_i32 s73, s73, 1
	s_mul_i32 s4, s73, s15
	s_mul_hi_u32 s5, s73, s14
	s_add_i32 s5, s5, s4
	s_mul_i32 s4, s73, s14
	s_add_u32 s56, s4, s12
	s_addc_u32 s57, s5, s72
	v_mov_b32_e32 v2, s99
	v_mov_b32_e32 v3, 0
	v_cmp_lt_i64_e64 s[4:5], s[56:57], v[2:3]
	v_add_u32_e32 v2, -1, v2
	v_cmp_gt_i64_e32 vcc, s[56:57], v[2:3]
	s_cbranch_vccnz .LBB0_91
	s_ashr_i32 s7, s56, 31
	s_lshr_b32 s7, s7, 29
	s_add_i32 s7, s56, s7
	s_ashr_i32 s17, s7, 3
	s_and_b32 s7, s7, -8
	s_sub_i32 s7, s56, s7
	s_cmp_lt_i32 s7, 0
	s_cselect_b32 s18, s74, 0x130
	s_mul_i32 s7, s18, s7
	s_add_i32 s7, s7, s17
	s_mul_hi_i32 s17, s7, 0x6bca1af3
	s_lshr_b32 s18, s17, 31
	s_ashr_i32 s17, s17, 6
	s_add_i32 s17, s17, s18
	s_lshl_b32 s18, s17, 2
	s_sub_i32 s19, 64, s18
	s_min_i32 s19, s19, 4
	s_abs_i32 s22, s19
	v_cvt_f32_u32_e32 v2, s22
	s_sub_i32 s42, 0, s22
	s_mulk_i32 s17, 0x98
	s_sub_i32 s7, s7, s17
	v_rcp_iflag_f32_e32 v2, v2
	s_abs_i32 s17, s7
	s_xor_b32 s23, s7, s19
	s_ashr_i32 s23, s23, 31
	v_mul_f32_e32 v2, 0x4f7ffffe, v2
	v_cvt_u32_f32_e32 v2, v2
	s_nop 0
	v_readfirstlane_b32 s43, v2
	s_mul_i32 s42, s42, s43
	s_mul_hi_u32 s42, s43, s42
	s_add_i32 s43, s43, s42
	s_mul_hi_u32 s42, s17, s43
	s_mul_i32 s43, s42, s22
	s_sub_i32 s17, s17, s43
	s_add_i32 s52, s42, 1
	s_sub_i32 s43, s17, s22
	s_cmp_ge_u32 s17, s22
	s_cselect_b32 s42, s52, s42
	s_cselect_b32 s17, s43, s17
	s_add_i32 s43, s42, 1
	s_cmp_ge_u32 s17, s22
	s_cselect_b32 s17, s43, s42
	s_xor_b32 s17, s17, s23
	s_sub_i32 s52, s17, s23
	s_mul_i32 s17, s52, s19
	s_sub_i32 s7, s7, s17
	s_add_i32 s54, s7, s18

; #define LAS __attribute__((address_space(3)))
; DI unsigned xb_xcc_id() { return (unsigned)__builtin_amdgcn_s_getreg((3 << 11) | 20) & 0xFu; }
; #define GSYNC() xcd_barrier((unsigned*)arg_ws(), bst)
; DI void xcd_barrier(unsigned* bar, volatile LAS unsigned* st) {
;     asm volatile("s_waitcnt vmcnt(0)" ::: "memory");
;     __syncthreads();
;     if (threadIdx.x == 0) {
;         __builtin_amdgcn_s_waitcnt(0);
;         const unsigned x = xb_xcc_id();
;         unsigned nloc = st[0], nx = st[1];
;         if (nloc == 0u) { xcd_barrier_complete(bar, x, nloc, nx); st[0] = nloc; st[1] = nx; }
; __global__ void __launch_bounds__(NTHREADS, 2) mega_fwd(Args a) {
;     ...
;                     GSYNC();
.LBB0_137:
	s_cmp_eq_u32 s98, 1
	s_cbranch_scc1 .Lwin_done
	s_mov_b64 s[6:7], s[0:1]
	s_waitcnt vmcnt(0)
	s_barrier
	s_and_saveexec_b64 s[4:5], s[10:11]
	s_cbranch_execz .LBB0_189
	v_mov_b32_e32 v1, s79
	s_load_dwordx2 s[6:7], s[6:7], 0xa8
	s_waitcnt vmcnt(0) expcnt(0) lgkmcnt(0)
	s_getreg_b32 s8, hwreg(HW_REG_XCC_ID, 0, 4)
	ds_read_b32 v3, v1
	v_mov_b32_e32 v1, s80
	ds_read_b32 v1, v1
	s_and_b32 s12, s8, 15
	s_waitcnt lgkmcnt(1)
	v_cmp_ne_u32_e32 vcc, 0, v3
	s_cbranch_vccnz .LBB0_153
	s_add_u32 s8, s6, 0x1000
	s_addc_u32 s9, s7, 0
	s_add_u32 s48, s6, 0x1100
	s_addc_u32 s49, s7, 0
	s_add_u32 s50, s6, 0x1200
	s_addc_u32 s51, s7, 0
	s_add_u32 s52, s6, 0x1300
	s_addc_u32 s53, s7, 0
	s_mov_b32 s17, 1
	s_branch .LBB0_141

; DI void ret_kv_phase(int l, unsigned char* lds_g, LAS unsigned char* lds) {
;     const int tid = opaque_tid(), lane = tid & 63, w = tid >> 6, fr = lane & 15, fq = lane >> 4;
;     const unsigned lbase = (unsigned)(size_t)lds_g;
;     const bf16_t* Z = (const bf16_t*)(arg_ws() + WS_Z); bf16_t* KV = (bf16_t*)(arg_ws() + WS_KV);
;     constexpr int OV = 0, OKF = 128 * RV_PITCH, OKB = OKF + 128 * RK_PITCH;
;     for (int item = opaque_bid(); item < GB * 4 * 32; item += gridDim.x) {
;         const int n = item & 31, h = (item >> 5) & 3, bl = item >> 7;
;         const size_t row0 = (size_t)bl * SEQ + n * 128;
;         const float de_f = arg_in(I_DEC)[(l * 2 + 0) * 4 + h], de_b = arg_in(I_DEC)[(l * 2 + 1) * 4 + h];
;         const float l2f = log1pf(-exp2f(-de_f)) * 1.44269504f, l2b = log1pf(-exp2f(-de_b)) * 1.44269504f;
; #pragma unroll
;         for (int i = 0; i < 8; ++i) { const int id = tid + 512 * i, r = id >> 5, ch = id & 31;
;             const u32x4 v = *(const u32x4*)(Z + (row0 + r) * INW + ZC_RV + h * 256 + ch * 8);
;             *(LAS u32x4*)(lds + OV + r * RV_PITCH + ch * 16) = v; }
; #pragma unroll
;         for (int i = 0; i < 4; ++i) { const int id = tid + 512 * i, r = id >> 4, ch = id & 15;
;             const u32x4 v = *(const u32x4*)(Z + (row0 + r) * INW + ZC_RK + h * 128 + ch * 8);
;             const float sf = fexp2(l2f * (float)(127 - r)), sb = fexp2(l2b * (float)r);
;             u32x4 f, b;
;             f.x = pk2(bflo(v.x) * sf, bfhi(v.x) * sf); f.y = pk2(bflo(v.y) * sf, bfhi(v.y) * sf); f.z = pk2(bflo(v.z) * sf, bfhi(v.z) * sf); f.w = pk2(bflo(v.w) * sf, bfhi(v.w) * sf);
;             b.x = pk2(bflo(v.x) * sb, bfhi(v.x) * sb); b.y = pk2(bflo(v.y) * sb, bfhi(v.y) * sb); b.z = pk2(bflo(v.z) * sb, bfhi(v.z) * sb); b.w = pk2(bflo(v.w) * sb, bfhi(v.w) * sb);
;             *(LAS u32x4*)(lds + OKF + r * RK_PITCH + ch * 16) = f; *(LAS u32x4*)(lds + OKB + r * RK_PITCH + ch * 16) = b; }
;         __syncthreads();
;         f32x4 acc[2][8][2];
; #pragma unroll
;         for (int d = 0; d < 2; ++d)
; #pragma unroll
;             for (int mt = 0; mt < 8; ++mt)
; #pragma unroll
;                 for (int nt = 0; nt < 2; ++nt) acc[d][mt][nt] = (f32x4){0.f, 0.f, 0.f, 0.f};
;         const int q = fr >> 2, p = fr & 3;
; #pragma unroll 1
;         for (int ks = 0; ks < 4; ++ks) {
;             const int tr0 = 32 * ks + 8 * fq + q;
.LBB0_189:
	s_or_b64 exec, exec, s[4:5]
	s_mov_b32 s98, 1
	s_movk_i32 s99, 0x980
	s_movk_i32 s100, 0x900
	s_branch .Lwin_again
.Lwin_done:
	v_mov_b32_e32 v2, v242
	s_mov_b64 s[8:9], s[0:1]
	s_mov_b64 s[6:7], s[0:1]
	s_mov_b32 s4, s2
	s_movk_i32 s101, 0x1ff
	s_cmp_lt_u32 s2, 0x80
	s_cselect_b32 s101, 0x7f, s101
	s_waitcnt lgkmcnt(0)
	s_barrier
	s_cmpk_gt_i32 s4, 0x1ff
	s_cbranch_scc1 .LBB0_194
	v_and_b32_e32 v3, 15, v2
	v_and_b32_e32 v1, 31, v2
	v_lshlrev_b32_e32 v8, 4, v3
	v_readlane_b32 s5, v255, 3
	s_waitcnt vmcnt(8)
	v_lshlrev_b32_e32 v4, 3, v1
	v_lshl_add_u32 v7, v1, 4, 0
	v_add_u32_e32 v1, s5, v8
	v_add_u32_e32 v160, s82, v8
	v_lshlrev_b32_e32 v8, 3, v2
	v_and_b32_e32 v14, 24, v8
	v_ashrrev_i32_e32 v8, 1, v2
	v_and_b32_e32 v8, 0xffffffe0, v8
	s_load_dwordx2 s[8:9], s[8:9], 0xa8
	s_nop 0
	s_load_dwordx2 s[22:23], s[6:7], 0xa8
	v_lshlrev_b32_e32 v6, 3, v3
	v_ashrrev_i32_e32 v9, 31, v8
	v_or_b32_e32 v8, v8, v3
	v_add_u32_e32 v3, 0x200, v2
	v_ashrrev_i32_e32 v146, 4, v2
	v_bfe_u32 v5, v2, 4, 2
	v_bfe_u32 v12, v2, 2, 2
	v_and_b32_e32 v13, 0xffffffc0, v2
	v_ashrrev_i32_e32 v130, 5, v2
	v_add_u32_e32 v17, 0x400, v2
	v_add_u32_e32 v19, 0x600, v2
	v_add_u32_e32 v21, 0x800, v2
	v_add_u32_e32 v22, 0xa00, v2
	v_add_u32_e32 v23, 0xc00, v2
	v_add_u32_e32 v24, 0xe00, v2
	v_sub_u32_e32 v2, 0x7f, v146
	v_ashrrev_i32_e32 v148, 4, v3
	v_cvt_f32_i32_e32 v161, v2
	v_sub_u32_e32 v2, 0x7f, v148
	v_ashrrev_i32_e32 v150, 4, v17
	v_cvt_f32_i32_e32 v164, v2
	v_sub_u32_e32 v2, 0x7f, v150
	v_ashrrev_i32_e32 v152, 4, v19
	v_lshlrev_b32_e32 v10, 3, v5
	v_mov_b32_e32 v11, v0
	v_cvt_f32_i32_e32 v167, v2
	v_sub_u32_e32 v2, 0x7f, v152
	s_waitcnt lgkmcnt(0)
	s_add_u32 s6, s8, 0x16c00000
	v_lshl_add_u64 v[10:11], s[22:23], 0, v[10:11]
	v_ashrrev_i32_e32 v132, 5, v3
	v_cvt_f32_i32_e32 v170, v2
	v_lshlrev_b64 v[2:3], 8, v[8:9]
	s_addc_u32 s7, s9, 0
	v_lshl_add_u64 v[2:3], v[10:11], 0, v[2:3]
	s_mov_b64 s[8:9], 0x29c00000
	v_cvt_f32_i32_e32 v162, v146
	v_cvt_f32_i32_e32 v165, v148
	v_cvt_f32_i32_e32 v168, v150
	v_cvt_f32_i32_e32 v171, v152
	v_lshl_add_u64 v[154:155], v[2:3], 0, s[8:9]
	v_mul_u32_u24_e32 v2, 0x880, v5
	v_mul_u32_u24_e32 v3, 0x110, v12
	v_ashrrev_i32_e32 v134, 5, v17
	v_ashrrev_i32_e32 v136, 5, v19
	v_ashrrev_i32_e32 v138, 5, v21
	v_ashrrev_i32_e32 v140, 5, v22
	v_ashrrev_i32_e32 v142, 5, v23
	v_ashrrev_i32_e32 v144, 5, v24
	v_add3_u32 v173, v2, v3, v14
	v_mul_u32_u24_e32 v2, 0x210, v12
	s_movk_i32 s5, 0x1080
	v_mul_lo_u32 v15, v130, s83
	v_mul_lo_u32 v16, v132, s83
	v_mul_lo_u32 v18, v134, s83
	v_mul_lo_u32 v20, v136, s83
	v_mul_lo_u32 v21, v138, s83
	v_mul_lo_u32 v22, v140, s83
	v_mul_lo_u32 v23, v142, s83
	v_mul_lo_u32 v24, v144, s83
	v_mad_u32_u24 v2, v5, s5, v2
	v_ashrrev_i32_e32 v131, 31, v130
	v_ashrrev_i32_e32 v133, 31, v132
	v_ashrrev_i32_e32 v135, 31, v134
	v_ashrrev_i32_e32 v137, 31, v136
	v_ashrrev_i32_e32 v139, 31, v138
	v_ashrrev_i32_e32 v141, 31, v140
	v_ashrrev_i32_e32 v143, 31, v142
	v_ashrrev_i32_e32 v145, 31, v144
	v_ashrrev_i32_e32 v147, 31, v146
	v_mul_lo_u32 v163, v146, s84
	v_ashrrev_i32_e32 v149, 31, v148
	v_mul_lo_u32 v166, v148, s84
	v_ashrrev_i32_e32 v151, 31, v150
	v_mul_lo_u32 v169, v150, s84
	v_ashrrev_i32_e32 v153, 31, v152
	v_mul_lo_u32 v172, v152, s84
	v_add3_u32 v174, v2, v13, v14
	v_lshlrev_b32_e32 v156, 1, v4
	v_add_u32_e32 v175, v7, v15
	v_add_u32_e32 v176, v7, v16
	v_add_u32_e32 v177, v7, v18
	v_add_u32_e32 v178, v7, v20
	v_add_u32_e32 v179, v7, v21
	v_add_u32_e32 v180, v7, v22
	v_add_u32_e32 v181, v7, v23
	v_add_u32_e32 v182, v7, v24
	v_lshlrev_b32_e32 v158, 1, v6

; DI f32x4 mfma16(bf16x8 a, bf16x8 b, f32x4 c) { return __builtin_amdgcn_mfma_f32_16x16x32_bf16(a, b, c, 0, 0, 0); }
; DI void ret_kv_phase(int l, unsigned char* lds_g, LAS unsigned char* lds) {
;     ...
;         const int q = fr >> 2, p = fr & 3;
; #pragma unroll 1
;         for (int ks = 0; ks < 4; ++ks) {
;             const int tr0 = 32 * ks + 8 * fq + q;
;             bf16x8 Bv[2];
; #pragma unroll
;             for (int nt = 0; nt < 2; ++nt) { const unsigned ad = lbase + OV + tr0 * RV_PITCH + (32 * w + 16 * nt + 4 * p) * 2; Bv[nt] = tr_frag(ad, ad + 4 * RV_PITCH); }
; #pragma unroll
;             for (int d = 0; d < 2; ++d) { const unsigned ad = lbase + (d ? OKB : OKF) + tr0 * RK_PITCH + (4 * p) * 2; bf16x8 Ak[8]; tr8(ad, ad + 4 * RK_PITCH, Ak);
; #pragma unroll
;                 for (int mt = 0; mt < 8; ++mt)
; #pragma unroll
;                     for (int nt = 0; nt < 2; ++nt) acc[d][mt][nt] = mfma16(Ak[mt], Bv[nt], acc[d][mt][nt]); }
;         }
.LBB0_192:
	s_cmp_lg_u32 0, -1
	s_cselect_b32 s8, 0, 0
	v_add_u32_e32 v183, s8, v157
	v_add_u32_e32 v188, 0x840, v183
	ds_read_b64_tr_b16 v[184:185], v183
	ds_read_b64_tr_b16 v[186:187], v188
	s_waitcnt lgkmcnt(0)
	v_add_u32_e32 v192, s8, v159
	v_add_u32_e32 v193, 32, v183
	v_add_u32_e32 v195, 0x860, v183
	ds_read_b64_tr_b16 v[188:189], v193
	ds_read_b64_tr_b16 v[190:191], v195
	s_waitcnt lgkmcnt(0)
	v_add_u32_e32 v204, 0x10800, v192
	v_add_u32_e32 v205, 0x10c40, v192
	ds_read_b64_tr_b16 v[214:215], v204
	ds_read_b64_tr_b16 v[216:217], v205
	ds_read_b64_tr_b16 v[210:211], v204 offset:32
	ds_read_b64_tr_b16 v[212:213], v205 offset:32
	ds_read_b64_tr_b16 v[206:207], v204 offset:64
	ds_read_b64_tr_b16 v[208:209], v205 offset:64
	ds_read_b64_tr_b16 v[200:201], v204 offset:96
	ds_read_b64_tr_b16 v[202:203], v205 offset:96
	s_waitcnt lgkmcnt(0)
	v_add_u32_e32 v183, 0x10880, v192
	v_mfma_f32_16x16x32_bf16 v[126:129], v[214:217], v[184:187], v[126:129]
	v_add_u32_e32 v193, 0x10cc0, v192
	s_add_i32 s5, s5, -1
	v_add_u32_e32 v159, 0x2200, v159
	v_mfma_f32_16x16x32_bf16 v[106:109], v[214:217], v[188:191], v[106:109]
	s_cmp_eq_u32 s5, 0
	v_add_u32_e32 v157, 0x4200, v157
	v_mfma_f32_16x16x32_bf16 v[122:125], v[210:213], v[184:187], v[122:125]
	v_mfma_f32_16x16x32_bf16 v[98:101], v[210:213], v[188:191], v[98:101]
	v_mfma_f32_16x16x32_bf16 v[118:121], v[206:209], v[184:187], v[118:121]
	v_mfma_f32_16x16x32_bf16 v[90:93], v[206:209], v[188:191], v[90:93]
	v_mfma_f32_16x16x32_bf16 v[114:117], v[200:203], v[184:187], v[114:117]
	v_mfma_f32_16x16x32_bf16 v[82:85], v[200:203], v[188:191], v[82:85]
	ds_read_b64_tr_b16 v[214:215], v183
	ds_read_b64_tr_b16 v[216:217], v193
	ds_read_b64_tr_b16 v[210:211], v183 offset:32
	ds_read_b64_tr_b16 v[212:213], v193 offset:32
	ds_read_b64_tr_b16 v[206:207], v183 offset:64
	ds_read_b64_tr_b16 v[208:209], v193 offset:64
	ds_read_b64_tr_b16 v[200:201], v183 offset:96
	ds_read_b64_tr_b16 v[202:203], v193 offset:96
	s_waitcnt lgkmcnt(0)
	v_add_u32_e32 v183, 0x19000, v192
	v_add_u32_e32 v193, 0x19440, v192
	v_mfma_f32_16x16x32_bf16 v[110:113], v[214:217], v[184:187], v[110:113]
	v_mfma_f32_16x16x32_bf16 v[78:81], v[214:217], v[188:191], v[78:81]
	v_mfma_f32_16x16x32_bf16 v[102:105], v[210:213], v[184:187], v[102:105]
	v_mfma_f32_16x16x32_bf16 v[74:77], v[210:213], v[188:191], v[74:77]
	v_mfma_f32_16x16x32_bf16 v[94:97], v[206:209], v[184:187], v[94:97]
	v_mfma_f32_16x16x32_bf16 v[70:73], v[206:209], v[188:191], v[70:73]
	v_mfma_f32_16x16x32_bf16 v[86:89], v[200:203], v[184:187], v[86:89]
	v_mfma_f32_16x16x32_bf16 v[66:69], v[200:203], v[188:191], v[66:69]
	ds_read_b64_tr_b16 v[214:215], v183
	ds_read_b64_tr_b16 v[216:217], v193
	ds_read_b64_tr_b16 v[210:211], v183 offset:32
	ds_read_b64_tr_b16 v[212:213], v193 offset:32
	ds_read_b64_tr_b16 v[206:207], v183 offset:64
	ds_read_b64_tr_b16 v[208:209], v193 offset:64
	ds_read_b64_tr_b16 v[200:201], v183 offset:96
	ds_read_b64_tr_b16 v[202:203], v193 offset:96
	s_waitcnt lgkmcnt(0)
	v_add_u32_e32 v183, 0x19080, v192
	v_add_u32_e32 v192, 0x194c0, v192
	v_mfma_f32_16x16x32_bf16 v[62:65], v[214:217], v[184:187], v[62:65]
	v_mfma_f32_16x16x32_bf16 v[34:37], v[214:217], v[188:191], v[34:37]
	v_mfma_f32_16x16x32_bf16 v[54:57], v[210:213], v[184:187], v[54:57]
	v_mfma_f32_16x16x32_bf16 v[26:29], v[210:213], v[188:191], v[26:29]
	v_mfma_f32_16x16x32_bf16 v[50:53], v[206:209], v[184:187], v[50:53]
	v_mfma_f32_16x16x32_bf16 v[18:21], v[206:209], v[188:191], v[18:21]
	v_mfma_f32_16x16x32_bf16 v[46:49], v[200:203], v[184:187], v[46:49]
	v_mfma_f32_16x16x32_bf16 v[14:17], v[200:203], v[188:191], v[14:17]
	ds_read_b64_tr_b16 v[214:215], v183
	ds_read_b64_tr_b16 v[216:217], v192
	ds_read_b64_tr_b16 v[210:211], v183 offset:32
	ds_read_b64_tr_b16 v[212:213], v192 offset:32
	ds_read_b64_tr_b16 v[206:207], v183 offset:64
	ds_read_b64_tr_b16 v[208:209], v192 offset:64
	ds_read_b64_tr_b16 v[200:201], v183 offset:96
	ds_read_b64_tr_b16 v[202:203], v192 offset:96
	s_waitcnt lgkmcnt(0)
	s_nop 0
	v_mfma_f32_16x16x32_bf16 v[38:41], v[214:217], v[184:187], v[38:41]
	v_mfma_f32_16x16x32_bf16 v[10:13], v[214:217], v[188:191], v[10:13]
	v_mfma_f32_16x16x32_bf16 v[30:33], v[210:213], v[184:187], v[30:33]
	v_mfma_f32_16x16x32_bf16 v[6:9], v[210:213], v[188:191], v[6:9]
	v_mfma_f32_16x16x32_bf16 v[22:25], v[206:209], v[184:187], v[22:25]
	v_mfma_f32_16x16x32_bf16 v[2:5], v[206:209], v[188:191], v[2:5]
	v_mfma_f32_16x16x32_bf16 v[58:61], v[200:203], v[184:187], v[58:61]
	v_mfma_f32_16x16x32_bf16 v[42:45], v[200:203], v[188:191], v[42:45]
	s_cbranch_scc0 .LBB0_192
; DI int opaque_bid() { int t = blockIdx.x; asm volatile("" : "+s"(t)); return t; }
; DI unsigned pk2(float lo, float hi) { unsigned r; asm("v_cvt_pk_bf16_f32 %0, %1, %2" : "=v"(r) : "v"(lo), "v"(hi)); return r; }
; DI void ret_kv_phase(int l, unsigned char* lds_g, LAS unsigned char* lds) {
;     ...
;     for (int item = opaque_bid(); item < GB * 4 * 32; item += gridDim.x) {
;     ...
; #pragma unroll
;         for (int d = 0; d < 2; ++d)
; #pragma unroll
;             for (int nt = 0; nt < 2; ++nt)
; #pragma unroll
;                 for (int mt = 0; mt < 8; ++mt)
;                     { u32x2 o; o.x = pk2(acc[d][mt][nt][0], acc[d][mt][nt][1]); o.y = pk2(acc[d][mt][nt][2], acc[d][mt][nt][3]);
;                       *(u32x2*)(KV + (((size_t)item * 2 + d) * 256 + 32 * w + 16 * nt + fr) * 128 + 16 * mt + 4 * fq) = o; }
;         __syncthreads();
	s_ashr_i32 s5, s4, 31
	s_lshl_b64 s[8:9], s[4:5], 17
	v_lshl_add_u64 v[184:185], v[154:155], 0, s[8:9]
	v_cvt_pk_bf16_f32 v86, v86, v87
	v_cvt_pk_bf16_f32 v87, v88, v89
	v_add_co_u32_e32 v88, vcc, s77, v184
	s_mov_b32 s5, 0x10000
	s_nop 0
	v_addc_co_u32_e32 v89, vcc, 0, v185, vcc
	v_cvt_pk_bf16_f32 v62, v62, v63
	v_cvt_pk_bf16_f32 v63, v64, v65
	v_add_co_u32_e32 v64, vcc, s5, v184
	v_cvt_pk_bf16_f32 v66, v66, v67
	s_mov_b32 s5, 0x11000
	s_nop 0
	v_addc_co_u32_e32 v65, vcc, 0, v185, vcc
	v_cvt_pk_bf16_f32 v22, v22, v23
	v_cvt_pk_bf16_f32 v23, v24, v25
	global_store_dwordx2 v[184:185], v[86:87], off offset:224
	v_cvt_pk_bf16_f32 v86, v106, v107
	v_cvt_pk_bf16_f32 v87, v108, v109
	v_cvt_pk_bf16_f32 v67, v68, v69
	global_store_dwordx2 v[88:89], v[66:67], off offset:224
	v_add_co_u32_e32 v66, vcc, s5, v184
	global_store_dwordx2 v[64:65], v[22:23], off offset:192
	v_cvt_pk_bf16_f32 v22, v58, v59
	v_cvt_pk_bf16_f32 v23, v60, v61
	s_add_i32 s4, s4, 0x80
	global_store_dwordx2 v[88:89], v[86:87], off
	v_cvt_pk_bf16_f32 v86, v98, v99
	v_cvt_pk_bf16_f32 v87, v100, v101
	v_addc_co_u32_e32 v67, vcc, 0, v185, vcc
	global_store_dwordx2 v[64:65], v[22:23], off offset:224
	v_cvt_pk_bf16_f32 v22, v34, v35
	v_cvt_pk_bf16_f32 v23, v36, v37
	v_cvt_pk_bf16_f32 v2, v2, v3
	v_cvt_pk_bf16_f32 v3, v4, v5
	s_cmp_gt_i32 s4, s101
	v_cvt_pk_bf16_f32 v126, v126, v127
	v_cvt_pk_bf16_f32 v127, v128, v129
	global_store_dwordx2 v[184:185], v[126:127], off
	v_cvt_pk_bf16_f32 v122, v122, v123
	v_cvt_pk_bf16_f32 v123, v124, v125
	global_store_dwordx2 v[184:185], v[122:123], off offset:32
	v_cvt_pk_bf16_f32 v118, v118, v119
	v_cvt_pk_bf16_f32 v119, v120, v121
	global_store_dwordx2 v[184:185], v[118:119], off offset:64
	v_cvt_pk_bf16_f32 v114, v114, v115
	v_cvt_pk_bf16_f32 v115, v116, v117
	global_store_dwordx2 v[184:185], v[114:115], off offset:96
	v_cvt_pk_bf16_f32 v110, v110, v111
	v_cvt_pk_bf16_f32 v111, v112, v113
	global_store_dwordx2 v[184:185], v[110:111], off offset:128
	v_cvt_pk_bf16_f32 v102, v102, v103
	v_cvt_pk_bf16_f32 v103, v104, v105
	global_store_dwordx2 v[184:185], v[102:103], off offset:160
	v_cvt_pk_bf16_f32 v94, v94, v95
	v_cvt_pk_bf16_f32 v95, v96, v97
	global_store_dwordx2 v[184:185], v[94:95], off offset:192
	global_store_dwordx2 v[88:89], v[86:87], off offset:32
	v_cvt_pk_bf16_f32 v86, v90, v91
	v_cvt_pk_bf16_f32 v87, v92, v93
	global_store_dwordx2 v[88:89], v[86:87], off offset:64
	v_cvt_pk_bf16_f32 v82, v82, v83
	v_cvt_pk_bf16_f32 v83, v84, v85
	global_store_dwordx2 v[88:89], v[82:83], off offset:96
	v_cvt_pk_bf16_f32 v78, v78, v79
	v_cvt_pk_bf16_f32 v79, v80, v81
	global_store_dwordx2 v[88:89], v[78:79], off offset:128
	v_cvt_pk_bf16_f32 v74, v74, v75
	v_cvt_pk_bf16_f32 v75, v76, v77
	global_store_dwordx2 v[88:89], v[74:75], off offset:160
	v_cvt_pk_bf16_f32 v70, v70, v71
	v_cvt_pk_bf16_f32 v71, v72, v73
	global_store_dwordx2 v[88:89], v[70:71], off offset:192
	global_store_dwordx2 v[66:67], v[62:63], off offset:-4096
	v_cvt_pk_bf16_f32 v54, v54, v55
	v_cvt_pk_bf16_f32 v55, v56, v57
	global_store_dwordx2 v[64:65], v[54:55], off offset:32
	v_cvt_pk_bf16_f32 v50, v50, v51
	v_cvt_pk_bf16_f32 v51, v52, v53
	global_store_dwordx2 v[64:65], v[50:51], off offset:64
	v_cvt_pk_bf16_f32 v46, v46, v47
	v_cvt_pk_bf16_f32 v47, v48, v49
	global_store_dwordx2 v[64:65], v[46:47], off offset:96
	v_cvt_pk_bf16_f32 v38, v38, v39
	v_cvt_pk_bf16_f32 v39, v40, v41
	global_store_dwordx2 v[64:65], v[38:39], off offset:128
	v_cvt_pk_bf16_f32 v30, v30, v31
	v_cvt_pk_bf16_f32 v31, v32, v33
	global_store_dwordx2 v[64:65], v[30:31], off offset:160
	global_store_dwordx2 v[66:67], v[22:23], off
	v_cvt_pk_bf16_f32 v22, v26, v27
	v_cvt_pk_bf16_f32 v23, v28, v29
	global_store_dwordx2 v[66:67], v[22:23], off offset:32
	v_cvt_pk_bf16_f32 v18, v18, v19
	v_cvt_pk_bf16_f32 v19, v20, v21
	global_store_dwordx2 v[66:67], v[18:19], off offset:64
	v_cvt_pk_bf16_f32 v14, v14, v15
	v_cvt_pk_bf16_f32 v15, v16, v17
	global_store_dwordx2 v[66:67], v[14:15], off offset:96
	v_cvt_pk_bf16_f32 v10, v10, v11
	v_cvt_pk_bf16_f32 v11, v12, v13
	global_store_dwordx2 v[66:67], v[10:11], off offset:128
	v_cvt_pk_bf16_f32 v6, v6, v7
	v_cvt_pk_bf16_f32 v7, v8, v9
	global_store_dwordx2 v[66:67], v[6:7], off offset:160
	global_store_dwordx2 v[66:67], v[2:3], off offset:192
	v_cvt_pk_bf16_f32 v2, v42, v43
	v_cvt_pk_bf16_f32 v3, v44, v45
	global_store_dwordx2 v[66:67], v[2:3], off offset:224
	s_barrier
	s_cbranch_scc0 .LBB0_191

; __global__ void __launch_bounds__(NTHREADS, 2) mega_fwd(Args a) {
	.amdhsa_kernel _Z8mega_fwd4Args
		.amdhsa_group_segment_fixed_size 0
		.amdhsa_private_segment_fixed_size 0
		.amdhsa_kernarg_size 432
		.amdhsa_user_sgpr_count 2
		.amdhsa_user_sgpr_dispatch_ptr 0
		.amdhsa_user_sgpr_queue_ptr 0
		.amdhsa_user_sgpr_kernarg_segment_ptr 1
		.amdhsa_user_sgpr_dispatch_id 0
		.amdhsa_user_sgpr_kernarg_preload_length 0
		.amdhsa_user_sgpr_kernarg_preload_offset 0
		.amdhsa_user_sgpr_private_segment_size 0
		.amdhsa_uses_dynamic_stack 0
		.amdhsa_enable_private_segment 0
		.amdhsa_system_sgpr_workgroup_id_x 1
		.amdhsa_system_sgpr_workgroup_id_y 0
		.amdhsa_system_sgpr_workgroup_id_z 0
		.amdhsa_system_sgpr_workgroup_info 0
		.amdhsa_system_vgpr_workitem_id 2
		.amdhsa_next_free_vgpr 256
		.amdhsa_next_free_sgpr 102
		.amdhsa_accum_offset 256
		.amdhsa_reserve_vcc 1
		.amdhsa_float_round_mode_32 0
		.amdhsa_float_round_mode_16_64 0
		.amdhsa_float_denorm_mode_32 3
		.amdhsa_float_denorm_mode_16_64 3
		.amdhsa_dx10_clamp 1
		.amdhsa_ieee_mode 1
		.amdhsa_fp16_overflow 0
		.amdhsa_tg_split 0
		.amdhsa_exception_fp_ieee_invalid_op 0
		.amdhsa_exception_fp_denorm_src 0
		.amdhsa_exception_fp_ieee_div_zero 0
		.amdhsa_exception_fp_ieee_overflow 0
		.amdhsa_exception_fp_ieee_underflow 0
		.amdhsa_exception_fp_ieee_inexact 0
		.amdhsa_exception_int_div_zero 0
	.end_amdhsa_kernel

; __global__ void __launch_bounds__(NTHREADS, 2) mega_fwd(Args a) {
amdhsa.kernels:
  - .agpr_count:     0
    .args:
      - .offset:         0
        .size:           176
        .value_kind:     by_value
      - .offset:         176
        .size:           4
        .value_kind:     hidden_block_count_x
      - .offset:         180
        .size:           4
        .value_kind:     hidden_block_count_y
      - .offset:         184
        .size:           4
        .value_kind:     hidden_block_count_z
      - .offset:         188
        .size:           2
        .value_kind:     hidden_group_size_x
      - .offset:         190
        .size:           2
        .value_kind:     hidden_group_size_y
      - .offset:         192
        .size:           2
        .value_kind:     hidden_group_size_z
      - .offset:         194
        .size:           2
        .value_kind:     hidden_remainder_x
      - .offset:         196
        .size:           2
        .value_kind:     hidden_remainder_y
      - .offset:         198
        .size:           2
        .value_kind:     hidden_remainder_z
      - .offset:         216
        .size:           8
        .value_kind:     hidden_global_offset_x
      - .offset:         224
        .size:           8
        .value_kind:     hidden_global_offset_y
      - .offset:         232
        .size:           8
        .value_kind:     hidden_global_offset_z
      - .offset:         240
        .size:           2
        .value_kind:     hidden_grid_dims
      - .offset:         264
        .size:           8
        .value_kind:     hidden_multigrid_sync_arg
      - .offset:         296
        .size:           4
        .value_kind:     hidden_dynamic_lds_size
    .group_segment_fixed_size: 0
    .kernarg_segment_align: 8
    .kernarg_segment_size: 432
    .language:       OpenCL C
    .language_version:
      - 2
      - 0
    .max_flat_workgroup_size: 512
    .name:           _Z8mega_fwd4Args
    .private_segment_fixed_size: 0
    .sgpr_count:     108
    .sgpr_spill_count: 11
    .symbol:         _Z8mega_fwd4Args.kd
    .uniform_work_group_size: 1
    .uses_dynamic_stack: false
    .vgpr_count:     256
    .vgpr_spill_count: 0
    .wavefront_size: 64
